# mLSTM q/k projection GEMM: workgroup order reversed (c -> 255-c) so the workgroups with two MLA-projection tiles get one A3 tile and vice versa (4-tile workgroups: 128 -> 32)
# speedup vs baseline: 1.0090x; 1.0090x over previous
.LBB0_886:
	v_readlane_b32 s0, v254, 5
	v_readlane_b32 s1, v254, 0
	v_readlane_b32 s98, v255, 41
	s_sub_i32 s99, 0xff, s1
	s_cmp_lg_u32 s98, 0
	s_cselect_b32 s1, s99, s1
	v_mov_b32_e32 v2, v163
	s_waitcnt vmcnt(0) lgkmcnt(0)
	s_barrier
	s_cmpk_gt_i32 s1, 0x17f
	v_readfirstlane_b32 s2, v2
	s_cbranch_scc1 .LBB0_898
	v_lshlrev_b32_e32 v0, 4, v2
	v_add_u32_e32 v4, 0x2000, v0
	v_ashrrev_i32_e32 v3, 31, v4
	v_lshrrev_b32_e32 v3, 22, v3
	v_add_u32_e32 v3, v4, v3
	v_ashrrev_i32_e32 v3, 10, v3
	v_readlane_b32 s4, v254, 25
	v_lshlrev_b32_e32 v5, 5, v3
	v_readlane_b32 s5, v254, 26
	v_and_b32_e32 v6, 32, v5
	v_mul_i32_i24_e32 v5, 0x400, v3
	s_load_dwordx2 s[4:5], s[4:5], 0x118
	v_sub_u32_e32 v4, v4, v5
	v_lshrrev_b32_e32 v5, 4, v4
	v_bitop3_b32 v5, v5, v4, 32 bitop3:0x6c
	v_ashrrev_i32_e32 v4, 31, v5
	v_lshrrev_b32_e32 v4, 26, v4
	s_waitcnt lgkmcnt(0)
	s_add_u32 s3, s4, 0x34b4000
	v_add_u32_e32 v7, v5, v4
	s_addc_u32 s24, s5, 0
	v_ashrrev_i32_e32 v4, 6, v7
	v_and_b32_e32 v7, 0xc0, v7
	s_add_u32 s25, s4, 0x634000
	v_sub_u32_e32 v5, v5, v7
	s_addc_u32 s26, s5, 0
	v_ashrrev_i16_sdwa v5, v171, sext(v5) dst_sel:DWORD dst_unused:UNUSED_PAD src0_sel:DWORD src1_sel:BYTE_0
	v_lshlrev_b32_e32 v7, 3, v3
	s_ashr_i32 s28, s1, 31
	v_bfe_i32 v5, v5, 0, 16
	v_and_b32_e32 v7, 0x3ffff0, v7
	s_lshr_b32 s4, s28, 29
	v_add_u32_e32 v6, v6, v5
	v_add_lshl_u32 v7, v4, v7, 10
	s_add_i32 s4, s1, s4
	s_ashr_i32 s5, s2, 6
	v_lshl_add_u32 v130, v6, 1, v7
	v_ashrrev_i32_e32 v6, 31, v2
	s_ashr_i32 s6, s4, 3
	s_and_b32 s4, s4, -8
	s_ashr_i32 s10, s2, 8
	s_lshl_b32 s27, s5, 10
	v_lshrrev_b32_e32 v6, 26, v6
	s_sub_i32 s4, s1, s4
	v_add_u32_e32 v6, v2, v6
	s_cmp_lt_i32 s4, 0
	v_ashrrev_i32_e32 v6, 6, v6
	s_cselect_b32 s7, 49, 48
	v_lshlrev_b32_e32 v7, 5, v6
	s_mul_i32 s4, s7, s4
	v_and_b32_e32 v9, 32, v7
	v_bfe_i32 v7, v2, 27, 1
	s_add_i32 s4, s4, s6
	v_lshrrev_b32_e32 v7, 22, v7
	s_ashr_i32 s6, s4, 31
	v_add_u32_e32 v7, v0, v7
	s_lshr_b32 s6, s6, 28
	v_and_b32_e32 v7, 0xfffffc00, v7
	s_add_i32 s6, s4, s6
	v_sub_u32_e32 v0, v0, v7
	s_ashr_i32 s7, s6, 4
	s_and_b32 s6, s6, 0xfff0
	v_lshrrev_b32_e32 v7, 4, v0
	s_sub_i32 s6, s4, s6
	v_bitop3_b32 v8, v7, v0, 32 bitop3:0x6c
	v_ashrrev_i32_e32 v0, 31, v0
	s_bfe_i32 s4, s6, 0x80000
	v_lshrrev_b32_e32 v0, 26, v0
	s_bfe_u32 s4, s4, 0x2000d
	v_add_u32_e32 v0, v8, v0
	s_add_i32 s8, s6, s4
	v_ashrrev_i32_e32 v7, 6, v0
	s_bfe_i32 s4, s8, 0x80000
	s_and_b32 s8, s8, 0xfc
	v_mul_i32_i24_e32 v0, 64, v7
	s_sub_i32 s6, s6, s8
	v_sub_u32_e32 v0, v8, v0
	s_lshl_b32 s7, s7, 2
	s_sext_i32_i16 s4, s4
	s_sext_i32_i8 s6, s6
	v_ashrrev_i16_sdwa v0, v171, sext(v0) dst_sel:DWORD dst_unused:UNUSED_PAD src0_sel:DWORD src1_sel:BYTE_0
	s_lshr_b32 s4, s4, 2
	s_add_i32 s6, s7, s6
	v_bfe_i32 v8, v0, 0, 16
	s_ashr_i32 s7, s6, 31
	s_bfe_i64 s[8:9], s[4:5], 0x100000
	v_add_u32_e32 v0, v9, v8
	v_lshlrev_b32_e32 v9, 3, v6
	s_lshl_b64 s[12:13], s[6:7], 18
	s_lshl_b64 s[8:9], s[8:9], 18
	v_and_b32_e32 v9, 0x3ffff0, v9
	s_add_u32 s8, s25, s8
	v_add_lshl_u32 v9, v7, v9, 10
	s_addc_u32 s9, s26, s9
	s_and_b32 s98, s4, 1
	s_lshl_b32 s98, s98, 9
	s_add_u32 s8, s8, s98
	s_addc_u32 s9, s9, 0
	s_add_i32 s29, s27, 0
	v_lshl_add_u32 v0, v0, 1, v9
	s_add_i32 m0, s29, 0x10000
	s_nop 0
	global_load_lds_dwordx4 v0, s[8:9]
	s_add_i32 m0, s29, 0x12000
	s_add_u32 s20, s3, s12
	global_load_lds_dwordx4 v130, s[8:9]
	s_addc_u32 s21, s24, s13
	s_add_u32 s20, s20, s98
	s_addc_u32 s21, s21, 0
	s_mov_b32 m0, s29
	s_add_i32 s30, s29, 0x2000
	global_load_lds_dwordx4 v0, s[20:21]
	s_mov_b32 m0, s30
	s_add_u32 s12, s8, 0x20000
	global_load_lds_dwordx4 v130, s[20:21]
	s_addc_u32 s13, s9, 0
	s_add_i32 m0, s29, 0x14000
	s_nop 0
	global_load_lds_dwordx4 v0, s[12:13]
	s_add_i32 m0, s29, 0x16000
	s_nop 0
	global_load_lds_dwordx4 v130, s[12:13]
	s_add_u32 s12, s20, 0x20000
	s_addc_u32 s13, s21, 0
	s_add_i32 s31, s29, 0x4000
	s_mov_b32 m0, s31
	s_add_i32 s34, s29, 0x6000
	global_load_lds_dwordx4 v0, s[12:13]
	s_mov_b32 m0, s34
	s_cmp_lg_u32 s10, 1
	global_load_lds_dwordx4 v130, s[12:13]
	s_cbranch_scc1 .LBB0_889
	s_barrier
